# R0 ctx rows: the 48 row pieces (ctx input + 11 partial slabs) fetched 24 at a time instead of one dependent round trip each; same add order
# speedup vs baseline: 1.0073x; 1.0073x over previous
; __device__ __forceinline__ void norm_rows_ctx(const float* cx, const float* slab, bf16_t* dst, int nrows, const f32x4 (&wv)[4], const f32x4 (&shv)[4], int gw, int ngw, int lane) {
;     for (int row = gw; row < nrows; row += ngw) {
;         const size_t ro = (size_t)row * D + 4 * lane;
;         f32x4 v[4]; float ss = 0.f;
; #pragma unroll
;         for (int j = 0; j < 4; ++j) { f32x4 a = *(const f32x4*)(cx + ro + 256 * j);
; #pragma unroll
;             for (int k = 0; k < 11; ++k) a += *(const f32x4*)(slab + (size_t)k * (TC * D) + ro + 256 * j);
;             v[j] = a; ss += (a[0] * a[0] + a[1] * a[1]) + (a[2] * a[2] + a[3] * a[3]); }
.LBB0_490:
	v_lshl_add_u64 v[44:45], s[6:7], 0, v[34:35]
	s_waitcnt lgkmcnt(0)
	v_lshl_add_u64 v[60:61], s[10:11], 0, v[34:35]
	s_mov_b32 s100, 0x1c900000
	s_mov_b32 s101, 0
	s_mov_b32 s98, 0x200000
	s_mov_b32 s99, 0
	v_lshl_add_u64 v[62:63], v[44:45], 0, s[100:101]
	v_lshl_add_u64 v[64:65], v[62:63], 0, s[98:99]
	v_lshl_add_u64 v[66:67], v[64:65], 0, s[98:99]
	v_lshl_add_u64 v[68:69], v[66:67], 0, s[98:99]
	v_lshl_add_u64 v[70:71], v[68:69], 0, s[98:99]
	v_lshl_add_u64 v[72:73], v[70:71], 0, s[98:99]
	v_lshl_add_u64 v[74:75], v[72:73], 0, s[98:99]
	v_lshl_add_u64 v[76:77], v[74:75], 0, s[98:99]
	v_lshl_add_u64 v[78:79], v[76:77], 0, s[98:99]
	v_lshl_add_u64 v[80:81], v[78:79], 0, s[98:99]
	v_lshl_add_u64 v[82:83], v[80:81], 0, s[98:99]
	s_mov_b32 s4, 0x8800000
	s_add_i32 s8, s8, s12
	v_lshl_add_u64 v[34:35], v[34:35], 0, s[86:87]
	s_cmpk_lt_i32 s8, 0x200
	global_load_dwordx4 v[96:99], v[60:61], off
	global_load_dwordx4 v[100:103], v[62:63], off
	global_load_dwordx4 v[104:107], v[64:65], off
	global_load_dwordx4 v[108:111], v[66:67], off
	global_load_dwordx4 v[112:115], v[68:69], off
	global_load_dwordx4 v[116:119], v[70:71], off
	global_load_dwordx4 v[120:123], v[72:73], off
	global_load_dwordx4 v[124:127], v[74:75], off
	global_load_dwordx4 v[130:133], v[76:77], off
	global_load_dwordx4 v[134:137], v[78:79], off
	global_load_dwordx4 v[138:141], v[80:81], off
	global_load_dwordx4 v[142:145], v[82:83], off
	global_load_dwordx4 v[146:149], v[60:61], off offset:1024
	global_load_dwordx4 v[150:153], v[62:63], off offset:1024
	global_load_dwordx4 v[158:161], v[64:65], off offset:1024
	global_load_dwordx4 v[162:165], v[66:67], off offset:1024
	global_load_dwordx4 v[170:173], v[68:69], off offset:1024
	global_load_dwordx4 v[178:181], v[70:71], off offset:1024
	global_load_dwordx4 v[182:185], v[72:73], off offset:1024
	global_load_dwordx4 v[186:189], v[74:75], off offset:1024
	global_load_dwordx4 v[190:193], v[76:77], off offset:1024
	global_load_dwordx4 v[194:197], v[78:79], off offset:1024
	global_load_dwordx4 v[198:201], v[80:81], off offset:1024
	global_load_dwordx4 v[202:205], v[82:83], off offset:1024
	s_waitcnt vmcnt(22)
	v_pk_add_f32 v[36:37], v[98:99], v[102:103]
	v_pk_add_f32 v[38:39], v[96:97], v[100:101]
	s_waitcnt vmcnt(21)
	v_pk_add_f32 v[36:37], v[36:37], v[106:107]
	v_pk_add_f32 v[38:39], v[38:39], v[104:105]
	s_waitcnt vmcnt(20)
	v_pk_add_f32 v[36:37], v[36:37], v[110:111]
	v_pk_add_f32 v[38:39], v[38:39], v[108:109]
	s_waitcnt vmcnt(19)
	v_pk_add_f32 v[36:37], v[36:37], v[114:115]
	v_pk_add_f32 v[38:39], v[38:39], v[112:113]
	s_waitcnt vmcnt(18)
	v_pk_add_f32 v[36:37], v[36:37], v[118:119]
	v_pk_add_f32 v[38:39], v[38:39], v[116:117]
	s_waitcnt vmcnt(17)
	v_pk_add_f32 v[36:37], v[36:37], v[122:123]
	v_pk_add_f32 v[38:39], v[38:39], v[120:121]
	s_waitcnt vmcnt(16)
	v_pk_add_f32 v[36:37], v[36:37], v[126:127]
	v_pk_add_f32 v[38:39], v[38:39], v[124:125]
	s_waitcnt vmcnt(15)
	v_pk_add_f32 v[36:37], v[36:37], v[132:133]
	v_pk_add_f32 v[38:39], v[38:39], v[130:131]
	s_waitcnt vmcnt(14)
	v_pk_add_f32 v[36:37], v[36:37], v[136:137]
	v_pk_add_f32 v[38:39], v[38:39], v[134:135]
	s_waitcnt vmcnt(13)
	v_pk_add_f32 v[36:37], v[36:37], v[140:141]
	v_pk_add_f32 v[38:39], v[38:39], v[138:139]
	s_waitcnt vmcnt(12)
	v_pk_add_f32 v[36:37], v[36:37], v[144:145]
	v_pk_add_f32 v[38:39], v[38:39], v[142:143]
	global_load_dwordx4 v[96:99], v[60:61], off offset:2048
	global_load_dwordx4 v[100:103], v[62:63], off offset:2048
	global_load_dwordx4 v[104:107], v[64:65], off offset:2048
	global_load_dwordx4 v[108:111], v[66:67], off offset:2048
	global_load_dwordx4 v[112:115], v[68:69], off offset:2048
	global_load_dwordx4 v[116:119], v[70:71], off offset:2048
	global_load_dwordx4 v[120:123], v[72:73], off offset:2048
	global_load_dwordx4 v[124:127], v[74:75], off offset:2048
	global_load_dwordx4 v[130:133], v[76:77], off offset:2048
	global_load_dwordx4 v[134:137], v[78:79], off offset:2048
	global_load_dwordx4 v[138:141], v[80:81], off offset:2048
	global_load_dwordx4 v[142:145], v[82:83], off offset:2048
	v_pk_mul_f32 v[206:207], v[36:37], v[36:37]
	v_pk_mul_f32 v[208:209], v[38:39], v[38:39]
	v_add_f32_e32 v84, v209, v208
	v_add_f32_e32 v85, v206, v207
	s_waitcnt vmcnt(22)
	v_pk_add_f32 v[40:41], v[148:149], v[152:153]
	v_pk_add_f32 v[42:43], v[146:147], v[150:151]
	s_waitcnt vmcnt(21)
	v_pk_add_f32 v[40:41], v[40:41], v[160:161]
	v_pk_add_f32 v[42:43], v[42:43], v[158:159]
	s_waitcnt vmcnt(20)
	v_pk_add_f32 v[40:41], v[40:41], v[164:165]
	v_pk_add_f32 v[42:43], v[42:43], v[162:163]
	s_waitcnt vmcnt(19)
	v_pk_add_f32 v[40:41], v[40:41], v[172:173]
	v_pk_add_f32 v[42:43], v[42:43], v[170:171]
	s_waitcnt vmcnt(18)
	v_pk_add_f32 v[40:41], v[40:41], v[180:181]
	v_pk_add_f32 v[42:43], v[42:43], v[178:179]
	s_waitcnt vmcnt(17)
	v_pk_add_f32 v[40:41], v[40:41], v[184:185]
	v_pk_add_f32 v[42:43], v[42:43], v[182:183]
	s_waitcnt vmcnt(16)
	v_pk_add_f32 v[40:41], v[40:41], v[188:189]
	v_pk_add_f32 v[42:43], v[42:43], v[186:187]
	s_waitcnt vmcnt(15)
	v_pk_add_f32 v[40:41], v[40:41], v[192:193]
	v_pk_add_f32 v[42:43], v[42:43], v[190:191]
	s_waitcnt vmcnt(14)
	v_pk_add_f32 v[40:41], v[40:41], v[196:197]
	v_pk_add_f32 v[42:43], v[42:43], v[194:195]
	s_waitcnt vmcnt(13)
	v_pk_add_f32 v[40:41], v[40:41], v[200:201]
	v_pk_add_f32 v[42:43], v[42:43], v[198:199]
	s_waitcnt vmcnt(12)
; __device__ __forceinline__ unsigned pk2(float lo, float hi) { unsigned r; asm("v_cvt_pk_bf16_f32 %0, %1, %2" : "=v"(r) : "v"(lo), "v"(hi)); return r; }
; __device__ __forceinline__ float wave_sum(float v, int lane) {
; #pragma unroll
;     for (int o = 1; o < 64; o <<= 1) v += __int_as_float(__builtin_amdgcn_ds_bpermute((lane ^ o) << 2, __float_as_int(v)));
;     return v;
; __device__ __forceinline__ void norm_rows_ctx(const float* cx, const float* slab, bf16_t* dst, int nrows, const f32x4 (&wv)[4], const f32x4 (&shv)[4], int gw, int ngw, int lane) {
;     ...
;         for (int j = 0; j < 4; ++j) { f32x4 a = *(const f32x4*)(cx + ro + 256 * j);
; #pragma unroll
;             for (int k = 0; k < 11; ++k) a += *(const f32x4*)(slab + (size_t)k * (TC * D) + ro + 256 * j);
;             v[j] = a; ss += (a[0] * a[0] + a[1] * a[1]) + (a[2] * a[2] + a[3] * a[3]); }
;         const float r = rsqrtf(wave_sum(ss, lane) * (1.0f / D) + EPS);
;         bf16_t* d = dst + ro;
; #pragma unroll
;         for (int j = 0; j < 4; ++j) { const f32x4 y = v[j] * r * wv[j] + shv[j]; u32x2 o; o.x = pk2(y[0], y[1]); o.y = pk2(y[2], y[3]); *(u32x2*)(d + 256 * j) = o; }
	v_pk_add_f32 v[40:41], v[40:41], v[204:205]
	v_pk_add_f32 v[42:43], v[42:43], v[202:203]
	global_load_dwordx4 v[146:149], v[60:61], off offset:3072
	global_load_dwordx4 v[150:153], v[62:63], off offset:3072
	global_load_dwordx4 v[158:161], v[64:65], off offset:3072
	global_load_dwordx4 v[162:165], v[66:67], off offset:3072
	global_load_dwordx4 v[170:173], v[68:69], off offset:3072
	global_load_dwordx4 v[178:181], v[70:71], off offset:3072
	global_load_dwordx4 v[182:185], v[72:73], off offset:3072
	global_load_dwordx4 v[186:189], v[74:75], off offset:3072
	global_load_dwordx4 v[190:193], v[76:77], off offset:3072
	global_load_dwordx4 v[194:197], v[78:79], off offset:3072
	global_load_dwordx4 v[198:201], v[80:81], off offset:3072
	global_load_dwordx4 v[202:205], v[82:83], off offset:3072
	v_pk_mul_f32 v[206:207], v[40:41], v[40:41]
	v_pk_mul_f32 v[208:209], v[42:43], v[42:43]
	v_add_f32_e32 v86, v209, v208
	v_add_f32_e32 v87, v206, v207
	s_waitcnt vmcnt(22)
	v_pk_add_f32 v[44:45], v[98:99], v[102:103]
	v_pk_add_f32 v[46:47], v[96:97], v[100:101]
	s_waitcnt vmcnt(21)
	v_pk_add_f32 v[44:45], v[44:45], v[106:107]
	v_pk_add_f32 v[46:47], v[46:47], v[104:105]
	s_waitcnt vmcnt(20)
	v_pk_add_f32 v[44:45], v[44:45], v[110:111]
	v_pk_add_f32 v[46:47], v[46:47], v[108:109]
	s_waitcnt vmcnt(19)
	v_pk_add_f32 v[44:45], v[44:45], v[114:115]
	v_pk_add_f32 v[46:47], v[46:47], v[112:113]
	s_waitcnt vmcnt(18)
	v_pk_add_f32 v[44:45], v[44:45], v[118:119]
	v_pk_add_f32 v[46:47], v[46:47], v[116:117]
	s_waitcnt vmcnt(17)
	v_pk_add_f32 v[44:45], v[44:45], v[122:123]
	v_pk_add_f32 v[46:47], v[46:47], v[120:121]
	s_waitcnt vmcnt(16)
	v_pk_add_f32 v[44:45], v[44:45], v[126:127]
	v_pk_add_f32 v[46:47], v[46:47], v[124:125]
	s_waitcnt vmcnt(15)
	v_pk_add_f32 v[44:45], v[44:45], v[132:133]
	v_pk_add_f32 v[46:47], v[46:47], v[130:131]
	s_waitcnt vmcnt(14)
	v_pk_add_f32 v[44:45], v[44:45], v[136:137]
	v_pk_add_f32 v[46:47], v[46:47], v[134:135]
	s_waitcnt vmcnt(13)
	v_pk_add_f32 v[44:45], v[44:45], v[140:141]
	v_pk_add_f32 v[46:47], v[46:47], v[138:139]
	s_waitcnt vmcnt(12)
	v_pk_add_f32 v[44:45], v[44:45], v[144:145]
	v_pk_add_f32 v[46:47], v[46:47], v[142:143]
	s_waitcnt vmcnt(10)
	v_pk_add_f32 v[48:49], v[148:149], v[152:153]
	v_pk_add_f32 v[50:51], v[146:147], v[150:151]
	s_waitcnt vmcnt(9)
	v_pk_add_f32 v[48:49], v[48:49], v[160:161]
	v_pk_add_f32 v[50:51], v[50:51], v[158:159]
	s_waitcnt vmcnt(8)
	v_pk_add_f32 v[48:49], v[48:49], v[164:165]
	v_pk_add_f32 v[50:51], v[50:51], v[162:163]
	s_waitcnt vmcnt(7)
	v_pk_add_f32 v[48:49], v[48:49], v[172:173]
	v_pk_add_f32 v[50:51], v[50:51], v[170:171]
	s_waitcnt vmcnt(6)
	v_pk_add_f32 v[48:49], v[48:49], v[180:181]
	v_pk_add_f32 v[50:51], v[50:51], v[178:179]
	s_waitcnt vmcnt(5)
	v_pk_add_f32 v[48:49], v[48:49], v[184:185]
	v_pk_add_f32 v[50:51], v[50:51], v[182:183]
	s_waitcnt vmcnt(4)
	v_pk_add_f32 v[48:49], v[48:49], v[188:189]
	v_pk_add_f32 v[50:51], v[50:51], v[186:187]
	s_waitcnt vmcnt(3)
	v_pk_add_f32 v[48:49], v[48:49], v[192:193]
	v_pk_add_f32 v[50:51], v[50:51], v[190:191]
	s_waitcnt vmcnt(2)
	v_pk_add_f32 v[48:49], v[48:49], v[196:197]
	v_pk_add_f32 v[50:51], v[50:51], v[194:195]
	s_waitcnt vmcnt(1)
	v_pk_add_f32 v[48:49], v[48:49], v[200:201]
	v_pk_add_f32 v[50:51], v[50:51], v[198:199]
	s_waitcnt vmcnt(0)
	v_pk_add_f32 v[48:49], v[48:49], v[204:205]
	v_pk_add_f32 v[50:51], v[50:51], v[202:203]
	v_pk_add_f32 v[60:61], v[84:85], v[84:85] op_sel:[0,1] op_sel_hi:[1,0]
	v_mul_f32_e32 v52, v50, v50
	v_mul_f32_e32 v59, v51, v51
	v_pk_add_f32 v[62:63], v[86:87], v[86:87] op_sel:[0,1] op_sel_hi:[1,0]
	v_mov_b32_e32 v61, v52
	v_mov_b32_e32 v63, v59
	v_mul_f32_e32 v52, v47, v47
	v_mul_f32_e32 v64, v48, v48
	v_pk_add_f32 v[60:61], v[60:61], v[62:63]
	v_pk_fma_f32 v[62:63], v[46:47], v[46:47], v[52:53] op_sel_hi:[1,1,0]
	v_mul_f32_e32 v52, v45, v45
	v_mul_f32_e32 v66, v49, v49
	v_mov_b32_e32 v63, v64
	v_pk_fma_f32 v[64:65], v[44:45], v[44:45], v[52:53] op_sel_hi:[1,1,0]
	s_nop 0
	v_mov_b32_e32 v65, v66
	v_pk_add_f32 v[62:63], v[62:63], v[64:65]
	s_nop 0
	v_pk_add_f32 v[60:61], v[60:61], v[62:63]
	s_nop 0
	v_add_f32_e32 v52, v60, v61
	ds_bpermute_b32 v59, v53, v52
	v_lshl_add_u64 v[60:61], s[6:7], 0, v[32:33]
	v_lshl_add_u64 v[32:33], v[32:33], 0, s[84:85]
	s_waitcnt lgkmcnt(0)
	v_add_f32_e32 v52, v52, v59
	ds_bpermute_b32 v59, v54, v52
	s_waitcnt lgkmcnt(0)
	v_add_f32_e32 v52, v52, v59
	ds_bpermute_b32 v59, v55, v52
	s_waitcnt lgkmcnt(0)
	v_add_f32_e32 v52, v52, v59
	ds_bpermute_b32 v59, v56, v52
	s_waitcnt lgkmcnt(0)
	v_add_f32_e32 v52, v52, v59
	ds_bpermute_b32 v59, v57, v52
	s_waitcnt lgkmcnt(0)
	v_add_f32_e32 v52, v52, v59
	ds_bpermute_b32 v59, v58, v52
	s_waitcnt lgkmcnt(0)
	v_add_f32_e32 v52, v52, v59
	v_fmamk_f32 v52, v52, 0x3a800000, v156
	v_cmp_gt_f32_e32 vcc, s13, v52
	v_mul_f32_e32 v59, 0x4b800000, v52
	s_nop 0
	v_cndmask_b32_e32 v52, v52, v59, vcc
	v_rsq_f32_e32 v52, v52
	s_nop 0
	v_mul_f32_e32 v59, 0x45800000, v52
	v_cndmask_b32_e32 v52, v52, v59, vcc
	v_pk_mul_f32 v[38:39], v[38:39], v[52:53] op_sel_hi:[1,0]
	v_pk_mul_f32 v[36:37], v[36:37], v[52:53] op_sel_hi:[1,0]
	v_pk_fma_f32 v[38:39], v[18:19], v[38:39], v[0:1]
	v_pk_fma_f32 v[36:37], v[16:17], v[36:37], v[2:3]
	v_cvt_pk_bf16_f32 v38, v38, v39
	v_pk_mul_f32 v[40:41], v[40:41], v[52:53] op_sel_hi:[1,0]
	v_cvt_pk_bf16_f32 v39, v36, v37
	v_add_co_u32_e32 v36, vcc, s4, v60
	v_pk_fma_f32 v[40:41], v[20:21], v[40:41], v[6:7]
	s_nop 0
	v_addc_co_u32_e32 v37, vcc, 0, v61, vcc
	global_store_dwordx2 v[36:37], v[38:39], off
	v_pk_mul_f32 v[38:39], v[42:43], v[52:53] op_sel_hi:[1,0]
	s_nop 0
	v_pk_fma_f32 v[38:39], v[22:23], v[38:39], v[4:5]
	s_nop 0
	v_cvt_pk_bf16_f32 v38, v38, v39
	v_cvt_pk_bf16_f32 v39, v40, v41
	global_store_dwordx2 v[36:37], v[38:39], off offset:512
	v_pk_mul_f32 v[38:39], v[46:47], v[52:53] op_sel_hi:[1,0]
	v_pk_mul_f32 v[40:41], v[44:45], v[52:53] op_sel_hi:[1,0]
	v_pk_fma_f32 v[38:39], v[26:27], v[38:39], v[8:9]
	v_pk_fma_f32 v[40:41], v[24:25], v[40:41], v[10:11]
	v_cvt_pk_bf16_f32 v38, v38, v39
	s_nop 0
	v_cvt_pk_bf16_f32 v39, v40, v41
	global_store_dwordx2 v[36:37], v[38:39], off offset:1024
	v_pk_mul_f32 v[38:39], v[50:51], v[52:53] op_sel_hi:[1,0]
	v_pk_mul_f32 v[40:41], v[48:49], v[52:53] op_sel_hi:[1,0]
	v_pk_fma_f32 v[38:39], v[30:31], v[38:39], v[12:13]
	v_pk_fma_f32 v[40:41], v[28:29], v[40:41], v[14:15]
	v_cvt_pk_bf16_f32 v38, v38, v39
	s_nop 0
	v_cvt_pk_bf16_f32 v39, v40, v41
	global_store_dwordx2 v[36:37], v[38:39], off offset:1536
	s_cbranch_scc1 .LBB0_490
